# static priority raise moved from waves 4-7 to waves 0-3 (older half) on top of the lean GEMM loops
# speedup vs baseline: 1.0033x; 1.0033x over previous
_Z10fwd_kernel6Params:
	v_readfirstlane_b32 s98, v0
	s_nop 3
	s_and_b32 s98, s98, 0x3ff
	s_cmp_ge_u32 s98, 0x100
	s_cbranch_scc1 .Lprio_skip
	s_setprio 1
